# class barriers at seams 6-8 now guarded by a run-time placement check (per-class XCC id census, device-wide barrier code kept as the fallback)
# speedup vs baseline: 1.0195x; 1.0034x over previous
_Z10fwd_kernel6Params:
	s_load_dwordx8 s[4:11], s[0:1], 0x80
	s_load_dwordx4 s[92:95], s[0:1], 0xa0
	s_load_dword s3, s[0:1], 0xb0
	v_and_b32_e32 v211, 0x3ff, v0
	s_mov_b32 s74, s2
	v_cmp_gt_u32_e32 vcc, 2, v211
	s_waitcnt lgkmcnt(0)
	v_writelane_b32 v254, s4, 0
	s_nop 1
	v_writelane_b32 v254, s5, 1
	v_writelane_b32 v254, s6, 2
	v_writelane_b32 v254, s7, 3
	v_writelane_b32 v254, s8, 4
	v_writelane_b32 v254, s9, 5
	v_writelane_b32 v254, s10, 6
	v_writelane_b32 v254, s11, 7
	s_add_u32 s4, s0, 0xa8
	s_addc_u32 s5, s1, 0
	s_and_saveexec_b64 s[6:7], vcc
	v_lshl_add_u32 v1, v211, 2, 0
	v_add_u32_e32 v1, 0x23700, v1
	v_mov_b32_e32 v2, 0
	ds_write_b32 v1, v2
	s_or_b64 exec, exec, s[6:7]
	s_waitcnt lgkmcnt(0)
	s_barrier
	v_writelane_b32 v255, 0, 41
	s_getreg_b32 s2, hwreg(HW_REG_XCC_ID, 0, 4)
	s_and_b32 s2, s2, 15
	v_cmp_eq_u32_e64 s[8:9], 0, v211
	s_mov_b64 s[6:7], exec
	s_nop 0
	v_writelane_b32 v254, s8, 8
	s_nop 1
	v_writelane_b32 v254, s9, 9
	s_and_b64 s[8:9], s[6:7], s[8:9]
	s_mov_b64 exec, s[8:9]
	s_cbranch_execz .LBB0_5
	s_mov_b64 s[8:9], exec
	v_mbcnt_lo_u32_b32 v1, s8, 0
	v_mbcnt_hi_u32_b32 v1, s9, v1
	v_cmp_eq_u32_e32 vcc, 0, v1
	s_and_b64 s[10:11], exec, vcc
	s_mov_b64 exec, s[10:11]
	s_cbranch_execz .LBB0_5
	s_lshl_b32 s10, s2, 8
	s_bcnt1_i32_b64 s8, s[8:9]
	v_mov_b32_e32 v1, s10
	v_mov_b32_e32 v2, s8
	global_atomic_add v1, v2, s[92:93] offset:1024
	s_and_b32 s10, s74, 7
	s_lshl_b32 s10, s10, 2
	s_add_u32 s10, s10, 0x5000
	v_mov_b32_e32 v1, s10
	s_add_u32 s10, s2, 1
	v_mov_b32_e32 v2, s10
	global_atomic_umax v1, v2, s[92:93]
	s_sub_u32 s10, 16, s2
	v_mov_b32_e32 v3, s10
	global_atomic_umax v1, v3, s[92:93] offset:64

.LBB0_130:
	s_waitcnt vmcnt(0)
	s_waitcnt vmcnt(0) lgkmcnt(0)
	s_barrier
	s_mov_b64 s[6:7], exec
	v_readlane_b32 s0, v254, 8
	v_readlane_b32 s1, v254, 9
	s_and_b64 s[0:1], s[6:7], s[0:1]
	s_mov_b64 exec, s[0:1]
	s_cbranch_execz .LBB0_182
	v_readlane_b32 s0, v255, 31
	s_cmp_lg_u32 s0, 0
	s_cbranch_scc1 .Lcls_chk_done
	s_and_b32 s0, s74, 7
	s_lshl_b32 s0, s0, 2
	v_mov_b32_e32 v2, s0
	s_add_u32 s2, s92, 0x5000
	s_addc_u32 s3, s93, 0
	global_load_dword v0, v2, s[2:3] sc1
	global_load_dword v1, v2, s[2:3] offset:64 sc1
	s_waitcnt vmcnt(0)
	v_add_u32_e32 v0, v0, v1
	s_nop 0
	v_readfirstlane_b32 s0, v0
	s_cmp_eq_u32 s0, 17
	s_cbranch_scc1 .Lcls_chk_done
	v_mov_b32_e32 v0, 1
	global_atomic_add v197, v0, s[2:3] offset:128
	s_waitcnt vmcnt(0)

.LBB0_738:
	s_waitcnt vmcnt(0)
	s_barrier
	s_mov_b64 s[6:7], exec
	v_readlane_b32 s0, v254, 8
	v_readlane_b32 s1, v254, 9
	s_and_b64 s[0:1], s[6:7], s[0:1]
	s_mov_b64 exec, s[0:1]
	s_cbranch_execz .LBB0_790
	v_readlane_b32 s0, v255, 41
	s_cmp_eq_u32 s0, 1
	s_cbranch_scc1 .Llb790_go
	s_cmp_eq_u32 s0, 2
	s_cbranch_scc1 .Llb790_global
	s_add_u32 s2, s92, 0x5000
	s_addc_u32 s3, s93, 0
	s_waitcnt vmcnt(0) lgkmcnt(0)
	global_load_dword v0, v197, s[2:3] offset:128 sc1
	s_waitcnt vmcnt(0)
	v_readfirstlane_b32 s0, v0
	s_cmp_eq_u32 s0, 0
	s_cselect_b32 s0, 1, 2
	s_nop 0
	v_writelane_b32 v255, s0, 41
	s_cmp_eq_u32 s0, 1
	s_cbranch_scc0 .Llb790_global
.Llb790_go:
	s_and_b32 s0, s74, 7
	s_lshl_b32 s0, s0, 8
	s_add_u32 s0, s0, 0x4000
	s_add_u32 s2, s92, s0
	s_addc_u32 s3, s93, 0
	v_mov_b32_e32 v0, 1
	s_waitcnt vmcnt(0) lgkmcnt(0)
	global_atomic_add v1, v197, v0, s[2:3] sc0
	buffer_inv sc1
	s_waitcnt vmcnt(0)
	v_readfirstlane_b32 s1, v1
	s_lshr_b32 s8, s1, 5
	s_and_b32 s1, s1, 31
	s_cmp_eq_u32 s1, 31
	s_cbranch_scc1 .Llb790_lead
	s_mov_b32 s9, 0

.Llb790_lead:
	global_atomic_add v197, v0, s[2:3] offset:2048
	s_waitcnt vmcnt(0)
	s_branch .LBB0_790

.LBB0_830:
	s_waitcnt vmcnt(0)
	s_waitcnt vmcnt(0)
	s_barrier
	s_mov_b64 s[6:7], exec
	v_readlane_b32 s0, v254, 8
	v_readlane_b32 s1, v254, 9
	s_and_b64 s[0:1], s[6:7], s[0:1]
	s_mov_b64 exec, s[0:1]
	s_cbranch_execz .LBB0_882
	v_readlane_b32 s0, v255, 41
	s_cmp_eq_u32 s0, 1
	s_cbranch_scc1 .Llb882_go
	s_cmp_eq_u32 s0, 2
	s_cbranch_scc1 .Llb882_global
	s_add_u32 s2, s92, 0x5000
	s_addc_u32 s3, s93, 0
	s_waitcnt vmcnt(0) lgkmcnt(0)
	global_load_dword v0, v197, s[2:3] offset:128 sc1
	s_waitcnt vmcnt(0)
	v_readfirstlane_b32 s0, v0
	s_cmp_eq_u32 s0, 0
	s_cselect_b32 s0, 1, 2
	s_nop 0
	v_writelane_b32 v255, s0, 41
	s_cmp_eq_u32 s0, 1
	s_cbranch_scc0 .Llb882_global
